# ZT moved to the unused 169 MiB workspace region (no ACT overlay, so no cross-XCC write-after-dirty hazard); norm1->chan seams local again (22 local + 7 grid)
# speedup vs baseline: 1.0084x; 1.0084x over previous
.LBB0_160:
	s_and_b64 vcc, exec, s[4:5]
	s_cbranch_vccz .LBB0_265
	s_waitcnt lgkmcnt(0)
	v_readlane_b32 s42, v239, 29
	s_cmp_gt_i32 s80, 0
	s_mov_b64 s[4:5], -1
	v_readlane_b32 s43, v239, 30
	s_cbranch_scc0 .LBB0_263
	s_cmp_gt_i32 s80, 1
	s_cbranch_scc0 .LBB0_227
	v_readlane_b32 s6, v239, 49
	v_readlane_b32 s7, v239, 50
	s_and_b64 vcc, exec, s[6:7]
	s_cbranch_vccz .LBB0_190
	s_cmpk_gt_i32 s78, 0xff
	v_readfirstlane_b32 s3, v210
	s_cbranch_scc1 .LBB0_189
	s_add_u32 s4, s42, 0x900000
	s_addc_u32 s5, s43, 0
	s_add_u32 s61, s42, 0xb00000
	s_addc_u32 s65, s43, 0
	s_add_u32 s66, s42, 0xa900000
	s_addc_u32 s67, s43, 0
	s_cmpk_gt_i32 s78, 0xff
	s_mov_b64 s[6:7], -1
	s_cbranch_scc0 .LBB0_167
	s_add_i32 s8, s78, 0xffffff00
	s_lshl_b32 s6, s8, 4
	s_and_b32 s70, s6, 0xffffff80
	s_and_b32 s50, s78, 7
	s_lshr_b32 s10, s8, 7
	s_mov_b32 s11, 0
	s_lshl_b32 s9, s50, 19
	s_lshl_b32 s6, s8, 5
	s_and_b32 s6, s6, 0xe00
	s_or_b32 s9, s9, s6
	s_lshl_b64 s[6:7], s[10:11], 22
	s_or_b32 s6, s6, s9
	s_lshl_b64 s[6:7], s[6:7], 1
	s_add_u32 s42, s66, s6
	s_addc_u32 s43, s67, s7
	s_bfe_u32 s8, s8, 0x10003
	s_lshl_b32 s8, s8, 20
	s_add_u32 s46, s4, s8
	s_addc_u32 s47, s5, 0
	s_mov_b32 s33, 8
	s_mov_b64 s[6:7], 0

.LBB0_232:
	v_readlane_b32 s10, v239, 29
	v_readlane_b32 s11, v239, 30
	s_add_u32 s68, s10, 0xa900000
	s_addc_u32 s69, s11, 0
	v_and_b32_e32 v14, 48, v211
	v_lshlrev_b32_e32 v15, 6, v211
	s_movk_i32 s9, 0x3c0
	s_lshl_b32 s7, s7, 5
	v_and_or_b32 v14, v15, s9, v14
	v_lshlrev_b32_e32 v15, 2, v211
	s_and_b32 s10, s7, 0x60
	s_add_i32 m0, s56, 0x18000
	v_lshl_add_u64 v[6:7], v[6:7], 0, s[0:1]
	s_lshl_b32 s70, s8, 6
	s_lshl_b32 s8, s8, 13
	v_and_b32_e32 v15, 32, v15
	s_lshl_b32 s7, s10, 7
	s_waitcnt vmcnt(2)
	s_barrier
	global_load_lds_dwordx4 v[6:7], off
	v_lshl_add_u64 v[4:5], v[4:5], 0, s[0:1]
	s_add_i32 m0, s56, 0x1a000
	s_add_i32 s71, s56, 0x8000
	s_add_i32 s72, s56, 0xa000
	v_bitop3_b32 v16, v14, s8, v15 bitop3:0xde
	global_load_lds_dwordx4 v[4:5], off
	v_lshl_add_u64 v[0:1], v[0:1], 0, s[0:1]
	s_mov_b32 m0, s71
	s_add_u32 s8, s42, 0x40080
	global_load_lds_dwordx4 v[0:1], off
	v_lshl_add_u64 v[0:1], v[2:3], 0, s[0:1]
	s_mov_b32 m0, s72
	s_addc_u32 s9, s43, 0
	global_load_lds_dwordx4 v[0:1], off
	s_add_i32 m0, s56, 0x1c000
	v_lshl_add_u64 v[0:1], s[8:9], 0, v[164:165]
	global_load_lds_dwordx4 v[0:1], off
	v_lshl_add_u64 v[0:1], s[8:9], 0, v[128:129]
	s_add_i32 m0, s56, 0x1e000
	s_cmpk_lt_u32 s6, 0x100
	global_load_lds_dwordx4 v[0:1], off
	v_lshlrev_b32_e32 v0, 12, v8
	v_and_b32_e32 v0, 0xffffe000, v0
	v_lshl_add_u32 v0, v9, 9, v0
	v_and_b32_e32 v1, 1, v8
	v_lshl_or_b32 v0, v1, 6, v0
	v_lshl_add_u32 v134, v10, 1, v0
	v_lshlrev_b32_e32 v0, 12, v12
	v_and_b32_e32 v0, 0xffffe000, v0
	s_waitcnt vmcnt(6)
	v_lshl_add_u32 v0, v11, 9, v0
	v_and_b32_e32 v1, 1, v12
	v_lshl_or_b32 v0, v1, 6, v0
	v_readlane_b32 s12, v240, 62
	v_bitop3_b32 v138, s7, v14, v15 bitop3:0xf6
	s_cselect_b64 s[6:7], -1, 0
	v_mov_b32_e32 v135, v165
	v_lshl_add_u32 v136, v13, 1, v0
	v_mov_b32_e32 v137, v165
	s_mov_b32 s73, 0
	v_add_u32_e32 v139, 0, v16
	v_readlane_b32 s13, v240, 63
	s_lshl_b32 s12, s10, 1
	s_mov_b64 s[14:15], s[42:43]
	s_mov_b64 s[10:11], s[38:39]
	s_barrier
	s_branch .LBB0_235
